# MLA loop: tail trim plus no exit test after the barrier of the second tile of each interval (the key-tile count is even, the loop can only end after a first tile)
# speedup vs baseline: 1.0030x; 1.0004x over previous
; #define STOREK(buf) do { LAS unsigned char* kb_ = lds + (buf) * ABUF; *(LAS u32x4*)(kb_ + (tid >> 3) * KP + (tid & 7) * 16) = kreg; \
;         if (VAR == 0 && tid < 256) *(LAS u32x4*)(kb_ + (tid >> 2) * KP + 128 + (tid & 3) * 16) = pereg; } while (0)
; #define STOREV(buf) do { *(LAS u32x4*)(lds + (buf) * ABUF + KT_BYTES + (tid >> 3) * VP + (tid & 7) * 16) = vreg; } while (0)
; #define SB() __builtin_amdgcn_sched_barrier(0)
; #define EX2(Pv, a, Wd) do { Pv[a] = __builtin_amdgcn_exp2f(Pv[a]); Pv[a + 1] = __builtin_amdgcn_exp2f(Pv[a + 1]); sacc += Pv[a]; sacc += Pv[a + 1]; Wd = cvtpk(Pv[a], Pv[a + 1]); } while (0)
; #define PV1(i, W) do { const bf16x8 pb_ = __builtin_bit_cast(bf16x8, W); if ((i) & 1) o1 = __builtin_amdgcn_mfma_f32_32x32x16_bf16(vf[i], pb_, o1, 0, 0, 0); else o0 = __builtin_amdgcn_mfma_f32_32x32x16_bf16(vf[i], pb_, o0, 0, 0, 0); } while (0)
; template <int VAR>
; __device__ __forceinline__ void attn_phase(LAS unsigned char* lds, const AttnP P, int vcu, int G, int wave_s) {
;     ...
;                 PV1(0, w0); EX2(pc1, 8, w3.x); VR1(4); SB();
;                 PV1(1, w0); EX2(pc1, 10, w3.y); VR1(5); SB();
;                 PV1(2, w1); EX2(pc1, 12, w3.z); VR1(6); SB();
;                 PV1(3, w1); EX2(pc1, 14, w3.w); VR1(7); SB();
;                 lrun += sacc;
;                 PV1(4, w2); MASK_TILE(pn0, pn1, t + 1); SB();
;                 PV1(5, w2); SB();
;                 PV1(6, w3); SB();
;                 PV1(7, w3); rmn = rowmax32(pn0, pn1); if (!USE_NEGM) rmn -= mref; SB();
;     ...
;             if (hn) { STOREK(t & 1); STOREV((t + 1) & 1); }
;             __syncthreads();
;             pc0 = pn0; pc1 = pn1; rmc = rmn; need_c = need_n;
.Lmla_p1_nope:
	s_waitcnt lgkmcnt(5)
	v_mfma_f32_32x32x16_bf16 v[2:17], v[186:189], v[214:217], v[2:17]
	ds_read_b128 v[186:189], v229 offset:19968
	v_max3_f32 v224, v224, v43, v44
	v_max3_f32 v225, v225, v59, v60
	v_max3_f32 v224, v224, v45, v46
	v_max3_f32 v225, v225, v61, v62
	v_add_u32_e32 v222, 0xb000, v173
	ds_write_b128 v222, v[202:205] offset:49152
	v_lshl_add_u32 v222, s13, 7, v168
	global_load_dwordx4 v[202:205], v222, s[56:57]
	s_waitcnt lgkmcnt(6)
	v_mfma_f32_32x32x16_bf16 v[18:33], v[190:193], v[214:217], v[18:33]
	ds_read_b128 v[190:193], v229 offset:13344
	v_max3_f32 v224, v224, v47, v48
	v_max3_f32 v225, v225, v63, v64
	v_max3_f32 v224, v224, v49, v65
	v_max_f32_e32 v224, v224, v225
	s_waitcnt lgkmcnt(6)
	v_mfma_f32_32x32x16_bf16 v[2:17], v[194:197], v[218:221], v[2:17]
	ds_read_b128 v[194:197], v229 offset:20000
	v_mov_b32_e32 v225, v224
	v_add_f32_e32 v1, v1, v164
	s_add_i32 s11, s11, 1
	v_permlane32_swap_b32_e32 v224, v225
	s_cmp_eq_u32 s9, s11
	v_max_f32_e32 v167, v224, v225
	v_cmp_lt_f32_e32 vcc, s66, v167
	s_waitcnt lgkmcnt(5)
	v_mfma_f32_32x32x16_bf16 v[18:33], v[198:201], v[218:221], v[18:33]
	s_waitcnt lgkmcnt(2)
	s_barrier
.Lmla_p2:
	s_cbranch_vccnz .Lmla_p2_resc

; #define STOREK(buf) do { LAS unsigned char* kb_ = lds + (buf) * ABUF; *(LAS u32x4*)(kb_ + (tid >> 3) * KP + (tid & 7) * 16) = kreg; \
;         if (VAR == 0 && tid < 256) *(LAS u32x4*)(kb_ + (tid >> 2) * KP + 128 + (tid & 3) * 16) = pereg; } while (0)
; #define STOREV(buf) do { *(LAS u32x4*)(lds + (buf) * ABUF + KT_BYTES + (tid >> 3) * VP + (tid & 7) * 16) = vreg; } while (0)
; #define SB() __builtin_amdgcn_sched_barrier(0)
; #define EX2(Pv, a, Wd) do { Pv[a] = __builtin_amdgcn_exp2f(Pv[a]); Pv[a + 1] = __builtin_amdgcn_exp2f(Pv[a + 1]); sacc += Pv[a]; sacc += Pv[a + 1]; Wd = cvtpk(Pv[a], Pv[a + 1]); } while (0)
; #define PV1(i, W) do { const bf16x8 pb_ = __builtin_bit_cast(bf16x8, W); if ((i) & 1) o1 = __builtin_amdgcn_mfma_f32_32x32x16_bf16(vf[i], pb_, o1, 0, 0, 0); else o0 = __builtin_amdgcn_mfma_f32_32x32x16_bf16(vf[i], pb_, o0, 0, 0, 0); } while (0)
; template <int VAR>
; __device__ __forceinline__ void attn_phase(LAS unsigned char* lds, const AttnP P, int vcu, int G, int wave_s) {
;     ...
;                 PV1(0, w0); EX2(pc1, 8, w3.x); VR1(4); SB();
;                 PV1(1, w0); EX2(pc1, 10, w3.y); VR1(5); SB();
;                 PV1(2, w1); EX2(pc1, 12, w3.z); VR1(6); SB();
;                 PV1(3, w1); EX2(pc1, 14, w3.w); VR1(7); SB();
;                 lrun += sacc;
;                 PV1(4, w2); MASK_TILE(pn0, pn1, t + 1); SB();
;                 PV1(5, w2); SB();
;                 PV1(6, w3); SB();
;                 PV1(7, w3); rmn = rowmax32(pn0, pn1); if (!USE_NEGM) rmn -= mref; SB();
;     ...
;             if (hn) { STOREK(t & 1); STOREV((t + 1) & 1); }
;             __syncthreads();
;             pc0 = pn0; pc1 = pn1; rmc = rmn; need_c = need_n;
.Lmla_p3_nope:
	s_waitcnt lgkmcnt(5)
	v_mfma_f32_32x32x16_bf16 v[2:17], v[186:189], v[214:217], v[2:17]
	ds_read_b128 v[186:189], v174 offset:6656
	v_max3_f32 v224, v224, v43, v44
	v_max3_f32 v225, v225, v59, v60
	v_max3_f32 v224, v224, v45, v46
	v_max3_f32 v225, v225, v61, v62
	ds_write_b128 v173, v[202:205] offset:35840
	v_lshl_add_u32 v222, s13, 7, v168
	global_load_dwordx4 v[202:205], v222, s[56:57]
	s_waitcnt lgkmcnt(6)
	v_mfma_f32_32x32x16_bf16 v[18:33], v[190:193], v[214:217], v[18:33]
	ds_read_b128 v[190:193], v174 offset:32
	v_max3_f32 v224, v224, v47, v48
	v_max3_f32 v225, v225, v63, v64
	v_max3_f32 v224, v224, v49, v65
	v_max_f32_e32 v224, v224, v225
	s_waitcnt lgkmcnt(6)
	v_mfma_f32_32x32x16_bf16 v[2:17], v[194:197], v[218:221], v[2:17]
	ds_read_b128 v[194:197], v174 offset:6688
	v_mov_b32_e32 v225, v224
	v_add_f32_e32 v1, v1, v164
	s_add_i32 s11, s11, 1
	v_permlane32_swap_b32_e32 v224, v225
	s_cmp_eq_u32 s9, s11
	v_max_f32_e32 v167, v224, v225
	v_cmp_lt_f32_e32 vcc, s66, v167
	s_waitcnt lgkmcnt(5)
	v_mfma_f32_32x32x16_bf16 v[18:33], v[198:201], v[218:221], v[18:33]
	s_waitcnt lgkmcnt(2)
	s_barrier
.Lmla_p4:
	s_cbranch_vccnz .Lmla_p4_resc

; #define STOREK(buf) do { LAS unsigned char* kb_ = lds + (buf) * ABUF; *(LAS u32x4*)(kb_ + (tid >> 3) * KP + (tid & 7) * 16) = kreg; \
;         if (VAR == 0 && tid < 256) *(LAS u32x4*)(kb_ + (tid >> 2) * KP + 128 + (tid & 3) * 16) = pereg; } while (0)
; #define STOREV(buf) do { *(LAS u32x4*)(lds + (buf) * ABUF + KT_BYTES + (tid >> 3) * VP + (tid & 7) * 16) = vreg; } while (0)
; #define SB() __builtin_amdgcn_sched_barrier(0)
; #define EX2(Pv, a, Wd) do { Pv[a] = __builtin_amdgcn_exp2f(Pv[a]); Pv[a + 1] = __builtin_amdgcn_exp2f(Pv[a + 1]); sacc += Pv[a]; sacc += Pv[a + 1]; Wd = cvtpk(Pv[a], Pv[a + 1]); } while (0)
; #define PV1(i, W) do { const bf16x8 pb_ = __builtin_bit_cast(bf16x8, W); if ((i) & 1) o1 = __builtin_amdgcn_mfma_f32_32x32x16_bf16(vf[i], pb_, o1, 0, 0, 0); else o0 = __builtin_amdgcn_mfma_f32_32x32x16_bf16(vf[i], pb_, o0, 0, 0, 0); } while (0)
; template <int VAR>
; __device__ __forceinline__ void attn_phase(LAS unsigned char* lds, const AttnP P, int vcu, int G, int wave_s) {
;     ...
;                 PV1(0, w0); EX2(pc1, 8, w3.x); VR1(4); SB();
;                 PV1(1, w0); EX2(pc1, 10, w3.y); VR1(5); SB();
;                 PV1(2, w1); EX2(pc1, 12, w3.z); VR1(6); SB();
;                 PV1(3, w1); EX2(pc1, 14, w3.w); VR1(7); SB();
;                 lrun += sacc;
;                 PV1(4, w2); MASK_TILE(pn0, pn1, t + 1); SB();
;                 PV1(5, w2); SB();
;                 PV1(6, w3); SB();
;                 PV1(7, w3); rmn = rowmax32(pn0, pn1); if (!USE_NEGM) rmn -= mref; SB();
;     ...
;             if (hn) { STOREK(t & 1); STOREV((t + 1) & 1); }
;             __syncthreads();
;             pc0 = pn0; pc1 = pn1; rmc = rmn; need_c = need_n;
.Lmla_p5_nope:
	s_waitcnt lgkmcnt(5)
	v_mfma_f32_32x32x16_bf16 v[2:17], v[186:189], v[214:217], v[2:17]
	ds_read_b128 v[186:189], v174 offset:51712
	v_max3_f32 v224, v224, v43, v44
	v_max3_f32 v225, v225, v59, v60
	v_max3_f32 v224, v224, v45, v46
	v_max3_f32 v225, v225, v61, v62
	v_add_u32_e32 v222, 0xb000, v173
	ds_write_b128 v222, v[202:205] offset:49152
	v_lshl_add_u32 v222, s13, 7, v168
	global_load_dwordx4 v[202:205], v222, s[56:57]
	s_waitcnt lgkmcnt(6)
	v_mfma_f32_32x32x16_bf16 v[18:33], v[190:193], v[214:217], v[18:33]
	ds_read_b128 v[190:193], v174 offset:45088
	v_max3_f32 v224, v224, v47, v48
	v_max3_f32 v225, v225, v63, v64
	v_max3_f32 v224, v224, v49, v65
	v_max_f32_e32 v224, v224, v225
	s_waitcnt lgkmcnt(6)
	v_mfma_f32_32x32x16_bf16 v[2:17], v[194:197], v[218:221], v[2:17]
	ds_read_b128 v[194:197], v174 offset:51744
	v_mov_b32_e32 v225, v224
	v_add_f32_e32 v1, v1, v164
	s_add_i32 s11, s11, 1
	v_permlane32_swap_b32_e32 v224, v225
	s_cmp_eq_u32 s9, s11
	v_max_f32_e32 v167, v224, v225
	v_cmp_lt_f32_e32 vcc, s66, v167
	s_waitcnt lgkmcnt(5)
	v_mfma_f32_32x32x16_bf16 v[18:33], v[198:201], v[218:221], v[18:33]
	s_waitcnt lgkmcnt(2)
	s_barrier
.Lmla_p6:
	s_cbranch_vccnz .Lmla_p6_resc

; #define STOREK(buf) do { LAS unsigned char* kb_ = lds + (buf) * ABUF; *(LAS u32x4*)(kb_ + (tid >> 3) * KP + (tid & 7) * 16) = kreg; \
;         if (VAR == 0 && tid < 256) *(LAS u32x4*)(kb_ + (tid >> 2) * KP + 128 + (tid & 3) * 16) = pereg; } while (0)
; #define STOREV(buf) do { *(LAS u32x4*)(lds + (buf) * ABUF + KT_BYTES + (tid >> 3) * VP + (tid & 7) * 16) = vreg; } while (0)
; #define SB() __builtin_amdgcn_sched_barrier(0)
; #define EX2(Pv, a, Wd) do { Pv[a] = __builtin_amdgcn_exp2f(Pv[a]); Pv[a + 1] = __builtin_amdgcn_exp2f(Pv[a + 1]); sacc += Pv[a]; sacc += Pv[a + 1]; Wd = cvtpk(Pv[a], Pv[a + 1]); } while (0)
; #define PV1(i, W) do { const bf16x8 pb_ = __builtin_bit_cast(bf16x8, W); if ((i) & 1) o1 = __builtin_amdgcn_mfma_f32_32x32x16_bf16(vf[i], pb_, o1, 0, 0, 0); else o0 = __builtin_amdgcn_mfma_f32_32x32x16_bf16(vf[i], pb_, o0, 0, 0, 0); } while (0)
; template <int VAR>
; __device__ __forceinline__ void attn_phase(LAS unsigned char* lds, const AttnP P, int vcu, int G, int wave_s) {
;     ...
;                 PV1(0, w0); EX2(pc1, 8, w3.x); VR1(4); SB();
;                 PV1(1, w0); EX2(pc1, 10, w3.y); VR1(5); SB();
;                 PV1(2, w1); EX2(pc1, 12, w3.z); VR1(6); SB();
;                 PV1(3, w1); EX2(pc1, 14, w3.w); VR1(7); SB();
;                 lrun += sacc;
;                 PV1(4, w2); MASK_TILE(pn0, pn1, t + 1); SB();
;                 PV1(5, w2); SB();
;                 PV1(6, w3); SB();
;                 PV1(7, w3); rmn = rowmax32(pn0, pn1); if (!USE_NEGM) rmn -= mref; SB();
;     ...
;             if (hn) { STOREK(t & 1); STOREV((t + 1) & 1); }
;             __syncthreads();
;             pc0 = pn0; pc1 = pn1; rmc = rmn; need_c = need_n;
.Lmla_p7_nope:
	s_waitcnt lgkmcnt(5)
	v_mfma_f32_32x32x16_bf16 v[2:17], v[186:189], v[214:217], v[2:17]
	ds_read_b128 v[186:189], v229 offset:33280
	v_max3_f32 v224, v224, v43, v44
	v_max3_f32 v225, v225, v59, v60
	v_max3_f32 v224, v224, v45, v46
	v_max3_f32 v225, v225, v61, v62
	ds_write_b128 v173, v[202:205] offset:35840
	v_lshl_add_u32 v222, s13, 7, v168
	global_load_dwordx4 v[202:205], v222, s[56:57]
	s_waitcnt lgkmcnt(6)
	v_mfma_f32_32x32x16_bf16 v[18:33], v[190:193], v[214:217], v[18:33]
	ds_read_b128 v[190:193], v229 offset:26656
	v_max3_f32 v224, v224, v47, v48
	v_max3_f32 v225, v225, v63, v64
	v_max3_f32 v224, v224, v49, v65
	v_max_f32_e32 v224, v224, v225
	s_waitcnt lgkmcnt(6)
	v_mfma_f32_32x32x16_bf16 v[2:17], v[194:197], v[218:221], v[2:17]
	ds_read_b128 v[194:197], v229 offset:33312
	v_mov_b32_e32 v225, v224
	v_add_f32_e32 v1, v1, v164
	s_add_i32 s11, s11, 1
	v_permlane32_swap_b32_e32 v224, v225
	s_cmp_eq_u32 s9, s11
	v_max_f32_e32 v167, v224, v225
	v_cmp_lt_f32_e32 vcc, s66, v167
	s_waitcnt lgkmcnt(5)
	v_mfma_f32_32x32x16_bf16 v[18:33], v[198:201], v[218:221], v[18:33]
	s_waitcnt lgkmcnt(2)
	s_barrier
.Lmla_p8:
	s_cbranch_vccnz .Lmla_p8_resc

; #define STOREK(buf) do { LAS unsigned char* kb_ = lds + (buf) * ABUF; *(LAS u32x4*)(kb_ + (tid >> 3) * KP + (tid & 7) * 16) = kreg; \
;         if (VAR == 0 && tid < 256) *(LAS u32x4*)(kb_ + (tid >> 2) * KP + 128 + (tid & 3) * 16) = pereg; } while (0)
; #define STOREV(buf) do { *(LAS u32x4*)(lds + (buf) * ABUF + KT_BYTES + (tid >> 3) * VP + (tid & 7) * 16) = vreg; } while (0)
; #define SB() __builtin_amdgcn_sched_barrier(0)
; #define EX2(Pv, a, Wd) do { Pv[a] = __builtin_amdgcn_exp2f(Pv[a]); Pv[a + 1] = __builtin_amdgcn_exp2f(Pv[a + 1]); sacc += Pv[a]; sacc += Pv[a + 1]; Wd = cvtpk(Pv[a], Pv[a + 1]); } while (0)
; #define PV1(i, W) do { const bf16x8 pb_ = __builtin_bit_cast(bf16x8, W); if ((i) & 1) o1 = __builtin_amdgcn_mfma_f32_32x32x16_bf16(vf[i], pb_, o1, 0, 0, 0); else o0 = __builtin_amdgcn_mfma_f32_32x32x16_bf16(vf[i], pb_, o0, 0, 0, 0); } while (0)
; template <int VAR>
; __device__ __forceinline__ void attn_phase(LAS unsigned char* lds, const AttnP P, int vcu, int G, int wave_s) {
;     ...
;                 PV1(0, w0); EX2(pc1, 8, w3.x); VR1(4); SB();
;                 PV1(1, w0); EX2(pc1, 10, w3.y); VR1(5); SB();
;                 PV1(2, w1); EX2(pc1, 12, w3.z); VR1(6); SB();
;                 PV1(3, w1); EX2(pc1, 14, w3.w); VR1(7); SB();
;                 lrun += sacc;
;                 PV1(4, w2); MASK_TILE(pn0, pn1, t + 1); SB();
;                 PV1(5, w2); SB();
;                 PV1(6, w3); SB();
;                 PV1(7, w3); rmn = rowmax32(pn0, pn1); if (!USE_NEGM) rmn -= mref; SB();
;     ...
;             if (hn) { STOREK(t & 1); STOREV((t + 1) & 1); }
;             __syncthreads();
;             pc0 = pn0; pc1 = pn1; rmc = rmn; need_c = need_n;
.Lmla_p9_nope:
	s_waitcnt lgkmcnt(5)
	v_mfma_f32_32x32x16_bf16 v[2:17], v[186:189], v[214:217], v[2:17]
	ds_read_b128 v[186:189], v174 offset:29184
	v_max3_f32 v224, v224, v43, v44
	v_max3_f32 v225, v225, v59, v60
	v_max3_f32 v224, v224, v45, v46
	v_max3_f32 v225, v225, v61, v62
	v_add_u32_e32 v222, 0xb000, v173
	ds_write_b128 v222, v[202:205] offset:49152
	v_lshl_add_u32 v222, s13, 7, v168
	global_load_dwordx4 v[202:205], v222, s[56:57]
	s_waitcnt lgkmcnt(6)
	v_mfma_f32_32x32x16_bf16 v[18:33], v[190:193], v[214:217], v[18:33]
	ds_read_b128 v[190:193], v174 offset:22560
	v_max3_f32 v224, v224, v47, v48
	v_max3_f32 v225, v225, v63, v64
	v_max3_f32 v224, v224, v49, v65
	v_max_f32_e32 v224, v224, v225
	s_waitcnt lgkmcnt(6)
	v_mfma_f32_32x32x16_bf16 v[2:17], v[194:197], v[218:221], v[2:17]
	ds_read_b128 v[194:197], v174 offset:29216
	v_mov_b32_e32 v225, v224
	v_add_f32_e32 v1, v1, v164
	s_add_i32 s11, s11, 1
	v_permlane32_swap_b32_e32 v224, v225
	s_cmp_eq_u32 s9, s11
	v_max_f32_e32 v167, v224, v225
	v_cmp_lt_f32_e32 vcc, s66, v167
	s_waitcnt lgkmcnt(5)
	v_mfma_f32_32x32x16_bf16 v[18:33], v[198:201], v[218:221], v[18:33]
	s_waitcnt lgkmcnt(2)
	s_barrier
.Lmla_p10:
	s_cbranch_vccnz .Lmla_p10_resc

; #define STOREK(buf) do { LAS unsigned char* kb_ = lds + (buf) * ABUF; *(LAS u32x4*)(kb_ + (tid >> 3) * KP + (tid & 7) * 16) = kreg; \
;         if (VAR == 0 && tid < 256) *(LAS u32x4*)(kb_ + (tid >> 2) * KP + 128 + (tid & 3) * 16) = pereg; } while (0)
; #define STOREV(buf) do { *(LAS u32x4*)(lds + (buf) * ABUF + KT_BYTES + (tid >> 3) * VP + (tid & 7) * 16) = vreg; } while (0)
; #define SB() __builtin_amdgcn_sched_barrier(0)
; #define EX2(Pv, a, Wd) do { Pv[a] = __builtin_amdgcn_exp2f(Pv[a]); Pv[a + 1] = __builtin_amdgcn_exp2f(Pv[a + 1]); sacc += Pv[a]; sacc += Pv[a + 1]; Wd = cvtpk(Pv[a], Pv[a + 1]); } while (0)
; #define PV1(i, W) do { const bf16x8 pb_ = __builtin_bit_cast(bf16x8, W); if ((i) & 1) o1 = __builtin_amdgcn_mfma_f32_32x32x16_bf16(vf[i], pb_, o1, 0, 0, 0); else o0 = __builtin_amdgcn_mfma_f32_32x32x16_bf16(vf[i], pb_, o0, 0, 0, 0); } while (0)
; template <int VAR>
; __device__ __forceinline__ void attn_phase(LAS unsigned char* lds, const AttnP P, int vcu, int G, int wave_s) {
;     ...
;                 PV1(0, w0); EX2(pc1, 8, w3.x); VR1(4); SB();
;                 PV1(1, w0); EX2(pc1, 10, w3.y); VR1(5); SB();
;                 PV1(2, w1); EX2(pc1, 12, w3.z); VR1(6); SB();
;                 PV1(3, w1); EX2(pc1, 14, w3.w); VR1(7); SB();
;                 lrun += sacc;
;                 PV1(4, w2); MASK_TILE(pn0, pn1, t + 1); SB();
;                 PV1(5, w2); SB();
;                 PV1(6, w3); SB();
;                 PV1(7, w3); rmn = rowmax32(pn0, pn1); if (!USE_NEGM) rmn -= mref; SB();
;     ...
;             if (hn) { STOREK(t & 1); STOREV((t + 1) & 1); }
;             __syncthreads();
;             pc0 = pn0; pc1 = pn1; rmc = rmn; need_c = need_n;
.Lmla_p11_nope:
	s_waitcnt lgkmcnt(5)
	v_mfma_f32_32x32x16_bf16 v[2:17], v[186:189], v[214:217], v[2:17]
	ds_read_b128 v[186:189], v229 offset:19968
	v_max3_f32 v224, v224, v43, v44
	v_max3_f32 v225, v225, v59, v60
	v_max3_f32 v224, v224, v45, v46
	v_max3_f32 v225, v225, v61, v62
	ds_write_b128 v173, v[202:205] offset:35840
	v_lshl_add_u32 v222, s13, 7, v168
	global_load_dwordx4 v[202:205], v222, s[56:57]
	s_waitcnt lgkmcnt(6)
	v_mfma_f32_32x32x16_bf16 v[18:33], v[190:193], v[214:217], v[18:33]
	ds_read_b128 v[190:193], v229 offset:13344
	v_max3_f32 v224, v224, v47, v48
	v_max3_f32 v225, v225, v63, v64
	v_max3_f32 v224, v224, v49, v65
	v_max_f32_e32 v224, v224, v225
	s_waitcnt lgkmcnt(6)
	v_mfma_f32_32x32x16_bf16 v[2:17], v[194:197], v[218:221], v[2:17]
	ds_read_b128 v[194:197], v229 offset:20000
	v_mov_b32_e32 v225, v224
	v_add_f32_e32 v1, v1, v164
	s_add_i32 s11, s11, 1
	v_permlane32_swap_b32_e32 v224, v225
	s_cmp_eq_u32 s9, s11
	v_max_f32_e32 v167, v224, v225
	v_cmp_lt_f32_e32 vcc, s66, v167
	s_waitcnt lgkmcnt(5)
	v_mfma_f32_32x32x16_bf16 v[18:33], v[198:201], v[218:221], v[18:33]
	s_waitcnt lgkmcnt(2)
	s_barrier
.Lmla_p12:
	s_cbranch_vccnz .Lmla_p12_resc

; #define STOREK(buf) do { LAS unsigned char* kb_ = lds + (buf) * ABUF; *(LAS u32x4*)(kb_ + (tid >> 3) * KP + (tid & 7) * 16) = kreg; \
;         if (VAR == 0 && tid < 256) *(LAS u32x4*)(kb_ + (tid >> 2) * KP + 128 + (tid & 3) * 16) = pereg; } while (0)
; #define STOREV(buf) do { *(LAS u32x4*)(lds + (buf) * ABUF + KT_BYTES + (tid >> 3) * VP + (tid & 7) * 16) = vreg; } while (0)
; #define SB() __builtin_amdgcn_sched_barrier(0)
; #define EX2(Pv, a, Wd) do { Pv[a] = __builtin_amdgcn_exp2f(Pv[a]); Pv[a + 1] = __builtin_amdgcn_exp2f(Pv[a + 1]); sacc += Pv[a]; sacc += Pv[a + 1]; Wd = cvtpk(Pv[a], Pv[a + 1]); } while (0)
; #define PV1(i, W) do { const bf16x8 pb_ = __builtin_bit_cast(bf16x8, W); if ((i) & 1) o1 = __builtin_amdgcn_mfma_f32_32x32x16_bf16(vf[i], pb_, o1, 0, 0, 0); else o0 = __builtin_amdgcn_mfma_f32_32x32x16_bf16(vf[i], pb_, o0, 0, 0, 0); } while (0)
; template <int VAR>
; __device__ __forceinline__ void attn_phase(LAS unsigned char* lds, const AttnP P, int vcu, int G, int wave_s) {
;     ...
;                 PV1(0, w0); EX2(pc1, 8, w3.x); VR1(4); SB();
;                 PV1(1, w0); EX2(pc1, 10, w3.y); VR1(5); SB();
;                 PV1(2, w1); EX2(pc1, 12, w3.z); VR1(6); SB();
;                 PV1(3, w1); EX2(pc1, 14, w3.w); VR1(7); SB();
;                 lrun += sacc;
;                 PV1(4, w2); MASK_TILE(pn0, pn1, t + 1); SB();
;                 PV1(5, w2); SB();
;                 PV1(6, w3); SB();
;                 PV1(7, w3); rmn = rowmax32(pn0, pn1); if (!USE_NEGM) rmn -= mref; SB();
;     ...
;             if (hn) { STOREK(t & 1); STOREV((t + 1) & 1); }
;             __syncthreads();
;             pc0 = pn0; pc1 = pn1; rmc = rmn; need_c = need_n;
.Lmla_p13_nope:
	s_waitcnt lgkmcnt(5)
	v_mfma_f32_32x32x16_bf16 v[2:17], v[186:189], v[214:217], v[2:17]
	ds_read_b128 v[186:189], v174 offset:6656
	v_max3_f32 v224, v224, v43, v44
	v_max3_f32 v225, v225, v59, v60
	v_max3_f32 v224, v224, v45, v46
	v_max3_f32 v225, v225, v61, v62
	v_add_u32_e32 v222, 0xb000, v173
	ds_write_b128 v222, v[202:205] offset:49152
	v_lshl_add_u32 v222, s13, 7, v168
	global_load_dwordx4 v[202:205], v222, s[56:57]
	s_waitcnt lgkmcnt(6)
	v_mfma_f32_32x32x16_bf16 v[18:33], v[190:193], v[214:217], v[18:33]
	ds_read_b128 v[190:193], v174 offset:32
	v_max3_f32 v224, v224, v47, v48
	v_max3_f32 v225, v225, v63, v64
	v_max3_f32 v224, v224, v49, v65
	v_max_f32_e32 v224, v224, v225
	s_waitcnt lgkmcnt(6)
	v_mfma_f32_32x32x16_bf16 v[2:17], v[194:197], v[218:221], v[2:17]
	ds_read_b128 v[194:197], v174 offset:6688
	v_mov_b32_e32 v225, v224
	v_add_f32_e32 v1, v1, v164
	s_add_i32 s11, s11, 1
	v_permlane32_swap_b32_e32 v224, v225
	s_cmp_eq_u32 s9, s11
	v_max_f32_e32 v167, v224, v225
	v_cmp_lt_f32_e32 vcc, s66, v167
	s_waitcnt lgkmcnt(5)
	v_mfma_f32_32x32x16_bf16 v[18:33], v[198:201], v[218:221], v[18:33]
	s_waitcnt lgkmcnt(2)
	s_barrier
.Lmla_p14:
	s_cbranch_vccnz .Lmla_p14_resc

; #define STOREK(buf) do { LAS unsigned char* kb_ = lds + (buf) * ABUF; *(LAS u32x4*)(kb_ + (tid >> 3) * KP + (tid & 7) * 16) = kreg; \
;         if (VAR == 0 && tid < 256) *(LAS u32x4*)(kb_ + (tid >> 2) * KP + 128 + (tid & 3) * 16) = pereg; } while (0)
; #define STOREV(buf) do { *(LAS u32x4*)(lds + (buf) * ABUF + KT_BYTES + (tid >> 3) * VP + (tid & 7) * 16) = vreg; } while (0)
; #define SB() __builtin_amdgcn_sched_barrier(0)
; #define EX2(Pv, a, Wd) do { Pv[a] = __builtin_amdgcn_exp2f(Pv[a]); Pv[a + 1] = __builtin_amdgcn_exp2f(Pv[a + 1]); sacc += Pv[a]; sacc += Pv[a + 1]; Wd = cvtpk(Pv[a], Pv[a + 1]); } while (0)
; #define PV1(i, W) do { const bf16x8 pb_ = __builtin_bit_cast(bf16x8, W); if ((i) & 1) o1 = __builtin_amdgcn_mfma_f32_32x32x16_bf16(vf[i], pb_, o1, 0, 0, 0); else o0 = __builtin_amdgcn_mfma_f32_32x32x16_bf16(vf[i], pb_, o0, 0, 0, 0); } while (0)
; template <int VAR>
; __device__ __forceinline__ void attn_phase(LAS unsigned char* lds, const AttnP P, int vcu, int G, int wave_s) {
;     ...
;                 PV1(0, w0); EX2(pc1, 8, w3.x); VR1(4); SB();
;                 PV1(1, w0); EX2(pc1, 10, w3.y); VR1(5); SB();
;                 PV1(2, w1); EX2(pc1, 12, w3.z); VR1(6); SB();
;                 PV1(3, w1); EX2(pc1, 14, w3.w); VR1(7); SB();
;                 lrun += sacc;
;                 PV1(4, w2); MASK_TILE(pn0, pn1, t + 1); SB();
;                 PV1(5, w2); SB();
;                 PV1(6, w3); SB();
;                 PV1(7, w3); rmn = rowmax32(pn0, pn1); if (!USE_NEGM) rmn -= mref; SB();
;     ...
;             if (hn) { STOREK(t & 1); STOREV((t + 1) & 1); }
;             __syncthreads();
;             pc0 = pn0; pc1 = pn1; rmc = rmn; need_c = need_n;
.Lmla_p15_nope:
	s_waitcnt lgkmcnt(5)
	v_mfma_f32_32x32x16_bf16 v[2:17], v[186:189], v[214:217], v[2:17]
	ds_read_b128 v[186:189], v174 offset:51712
	v_max3_f32 v224, v224, v43, v44
	v_max3_f32 v225, v225, v59, v60
	v_max3_f32 v224, v224, v45, v46
	v_max3_f32 v225, v225, v61, v62
	ds_write_b128 v173, v[202:205] offset:35840
	v_lshl_add_u32 v222, s13, 7, v168
	global_load_dwordx4 v[202:205], v222, s[56:57]
	s_waitcnt lgkmcnt(6)
	v_mfma_f32_32x32x16_bf16 v[18:33], v[190:193], v[214:217], v[18:33]
	ds_read_b128 v[190:193], v174 offset:45088
	v_max3_f32 v224, v224, v47, v48
	v_max3_f32 v225, v225, v63, v64
	v_max3_f32 v224, v224, v49, v65
	v_max_f32_e32 v224, v224, v225
	s_waitcnt lgkmcnt(6)
	v_mfma_f32_32x32x16_bf16 v[2:17], v[194:197], v[218:221], v[2:17]
	ds_read_b128 v[194:197], v174 offset:51744
	v_mov_b32_e32 v225, v224
	v_add_f32_e32 v1, v1, v164
	s_add_i32 s11, s11, 1
	v_permlane32_swap_b32_e32 v224, v225
	s_cmp_eq_u32 s9, s11
	v_max_f32_e32 v167, v224, v225
	v_cmp_lt_f32_e32 vcc, s66, v167
	s_waitcnt lgkmcnt(5)
	v_mfma_f32_32x32x16_bf16 v[18:33], v[198:201], v[218:221], v[18:33]
	s_waitcnt lgkmcnt(2)
	s_barrier
.Lmla_p16:
	s_cbranch_vccnz .Lmla_p16_resc

; #define STOREK(buf) do { LAS unsigned char* kb_ = lds + (buf) * ABUF; *(LAS u32x4*)(kb_ + (tid >> 3) * KP + (tid & 7) * 16) = kreg; \
;         if (VAR == 0 && tid < 256) *(LAS u32x4*)(kb_ + (tid >> 2) * KP + 128 + (tid & 3) * 16) = pereg; } while (0)
; #define STOREV(buf) do { *(LAS u32x4*)(lds + (buf) * ABUF + KT_BYTES + (tid >> 3) * VP + (tid & 7) * 16) = vreg; } while (0)
; #define SB() __builtin_amdgcn_sched_barrier(0)
; #define EX2(Pv, a, Wd) do { Pv[a] = __builtin_amdgcn_exp2f(Pv[a]); Pv[a + 1] = __builtin_amdgcn_exp2f(Pv[a + 1]); sacc += Pv[a]; sacc += Pv[a + 1]; Wd = cvtpk(Pv[a], Pv[a + 1]); } while (0)
; #define PV1(i, W) do { const bf16x8 pb_ = __builtin_bit_cast(bf16x8, W); if ((i) & 1) o1 = __builtin_amdgcn_mfma_f32_32x32x16_bf16(vf[i], pb_, o1, 0, 0, 0); else o0 = __builtin_amdgcn_mfma_f32_32x32x16_bf16(vf[i], pb_, o0, 0, 0, 0); } while (0)
; template <int VAR>
; __device__ __forceinline__ void attn_phase(LAS unsigned char* lds, const AttnP P, int vcu, int G, int wave_s) {
;     ...
;                 PV1(0, w0); EX2(pc1, 8, w3.x); VR1(4); SB();
;                 PV1(1, w0); EX2(pc1, 10, w3.y); VR1(5); SB();
;                 PV1(2, w1); EX2(pc1, 12, w3.z); VR1(6); SB();
;                 PV1(3, w1); EX2(pc1, 14, w3.w); VR1(7); SB();
;                 lrun += sacc;
;                 PV1(4, w2); MASK_TILE(pn0, pn1, t + 1); SB();
;                 PV1(5, w2); SB();
;                 PV1(6, w3); SB();
;                 PV1(7, w3); rmn = rowmax32(pn0, pn1); if (!USE_NEGM) rmn -= mref; SB();
;     ...
;             if (hn) { STOREK(t & 1); STOREV((t + 1) & 1); }
;             __syncthreads();
;             pc0 = pn0; pc1 = pn1; rmc = rmn; need_c = need_n;
.Lmla_p17_nope:
	s_waitcnt lgkmcnt(5)
	v_mfma_f32_32x32x16_bf16 v[2:17], v[186:189], v[214:217], v[2:17]
	ds_read_b128 v[186:189], v229 offset:33280
	v_max3_f32 v224, v224, v43, v44
	v_max3_f32 v225, v225, v59, v60
	v_max3_f32 v224, v224, v45, v46
	v_max3_f32 v225, v225, v61, v62
	v_add_u32_e32 v222, 0xb000, v173
	ds_write_b128 v222, v[202:205] offset:49152
	v_lshl_add_u32 v222, s13, 7, v168
	global_load_dwordx4 v[202:205], v222, s[56:57]
	s_waitcnt lgkmcnt(6)
	v_mfma_f32_32x32x16_bf16 v[18:33], v[190:193], v[214:217], v[18:33]
	ds_read_b128 v[190:193], v229 offset:26656
	v_max3_f32 v224, v224, v47, v48
	v_max3_f32 v225, v225, v63, v64
	v_max3_f32 v224, v224, v49, v65
	v_max_f32_e32 v224, v224, v225
	s_waitcnt lgkmcnt(6)
	v_mfma_f32_32x32x16_bf16 v[2:17], v[194:197], v[218:221], v[2:17]
	ds_read_b128 v[194:197], v229 offset:33312
	v_mov_b32_e32 v225, v224
	v_add_f32_e32 v1, v1, v164
	s_add_i32 s11, s11, 1
	v_permlane32_swap_b32_e32 v224, v225
	s_cmp_eq_u32 s9, s11
	v_max_f32_e32 v167, v224, v225
	v_cmp_lt_f32_e32 vcc, s66, v167
	s_waitcnt lgkmcnt(5)
	v_mfma_f32_32x32x16_bf16 v[18:33], v[198:201], v[218:221], v[18:33]
	s_waitcnt lgkmcnt(2)
	s_barrier
.Lmla_p18:
	s_cbranch_vccnz .Lmla_p18_resc

; #define STOREK(buf) do { LAS unsigned char* kb_ = lds + (buf) * ABUF; *(LAS u32x4*)(kb_ + (tid >> 3) * KP + (tid & 7) * 16) = kreg; \
;         if (VAR == 0 && tid < 256) *(LAS u32x4*)(kb_ + (tid >> 2) * KP + 128 + (tid & 3) * 16) = pereg; } while (0)
; #define STOREV(buf) do { *(LAS u32x4*)(lds + (buf) * ABUF + KT_BYTES + (tid >> 3) * VP + (tid & 7) * 16) = vreg; } while (0)
; #define SB() __builtin_amdgcn_sched_barrier(0)
; #define EX2(Pv, a, Wd) do { Pv[a] = __builtin_amdgcn_exp2f(Pv[a]); Pv[a + 1] = __builtin_amdgcn_exp2f(Pv[a + 1]); sacc += Pv[a]; sacc += Pv[a + 1]; Wd = cvtpk(Pv[a], Pv[a + 1]); } while (0)
; #define PV1(i, W) do { const bf16x8 pb_ = __builtin_bit_cast(bf16x8, W); if ((i) & 1) o1 = __builtin_amdgcn_mfma_f32_32x32x16_bf16(vf[i], pb_, o1, 0, 0, 0); else o0 = __builtin_amdgcn_mfma_f32_32x32x16_bf16(vf[i], pb_, o0, 0, 0, 0); } while (0)
; template <int VAR>
; __device__ __forceinline__ void attn_phase(LAS unsigned char* lds, const AttnP P, int vcu, int G, int wave_s) {
;     ...
;                 PV1(0, w0); EX2(pc1, 8, w3.x); VR1(4); SB();
;                 PV1(1, w0); EX2(pc1, 10, w3.y); VR1(5); SB();
;                 PV1(2, w1); EX2(pc1, 12, w3.z); VR1(6); SB();
;                 PV1(3, w1); EX2(pc1, 14, w3.w); VR1(7); SB();
;                 lrun += sacc;
;                 PV1(4, w2); MASK_TILE(pn0, pn1, t + 1); SB();
;                 PV1(5, w2); SB();
;                 PV1(6, w3); SB();
;                 PV1(7, w3); rmn = rowmax32(pn0, pn1); if (!USE_NEGM) rmn -= mref; SB();
;     ...
;             if (hn) { STOREK(t & 1); STOREV((t + 1) & 1); }
;             __syncthreads();
;             pc0 = pn0; pc1 = pn1; rmc = rmn; need_c = need_n;
.Lmla_p19_nope:
	s_waitcnt lgkmcnt(5)
	v_mfma_f32_32x32x16_bf16 v[2:17], v[186:189], v[214:217], v[2:17]
	ds_read_b128 v[186:189], v174 offset:29184
	v_max3_f32 v224, v224, v43, v44
	v_max3_f32 v225, v225, v59, v60
	v_max3_f32 v224, v224, v45, v46
	v_max3_f32 v225, v225, v61, v62
	ds_write_b128 v173, v[202:205] offset:35840
	v_lshl_add_u32 v222, s13, 7, v168
	global_load_dwordx4 v[202:205], v222, s[56:57]
	s_waitcnt lgkmcnt(6)
	v_mfma_f32_32x32x16_bf16 v[18:33], v[190:193], v[214:217], v[18:33]
	ds_read_b128 v[190:193], v174 offset:22560
	v_max3_f32 v224, v224, v47, v48
	v_max3_f32 v225, v225, v63, v64
	v_max3_f32 v224, v224, v49, v65
	v_max_f32_e32 v224, v224, v225
	s_waitcnt lgkmcnt(6)
	v_mfma_f32_32x32x16_bf16 v[2:17], v[194:197], v[218:221], v[2:17]
	ds_read_b128 v[194:197], v174 offset:29216
	v_mov_b32_e32 v225, v224
	v_add_f32_e32 v1, v1, v164
	s_add_i32 s11, s11, 1
	v_permlane32_swap_b32_e32 v224, v225
	s_cmp_eq_u32 s9, s11
	v_max_f32_e32 v167, v224, v225
	v_cmp_lt_f32_e32 vcc, s66, v167
	s_waitcnt lgkmcnt(5)
	v_mfma_f32_32x32x16_bf16 v[18:33], v[198:201], v[218:221], v[18:33]
	s_waitcnt lgkmcnt(2)
	s_barrier
	s_branch .Lmla_p0
